# adds: P6 tail tiles before its GEMM units; mini-tile K loads batched (1-2 round trips instead of 8-16); barrier counter loads batched; fast y_s epilogue also in leftover copy
# speedup vs baseline: 1.0248x; 1.0026x over previous
; template <int MODE  >
; __device__ __forceinline__ void mini_tile(const Args& a, LAS unsigned char* lds, int tile, int tid) {
;     ...
;     for (int s = 0; s < 8; ++s) {
;         const bf16x8 a1 = *(const bf16x8*)(A1 + 16 * s), b10 = *(const bf16x8*)(B1 + 16 * s), b11 = *(const bf16x8*)(B1 + 32 * LDA + 16 * s);
;         acc[0][0] = __builtin_amdgcn_mfma_f32_32x32x16_bf16(a1, b10, acc[0][0], 0, 0, 0);
;         acc[0][1] = __builtin_amdgcn_mfma_f32_32x32x16_bf16(a1, b11, acc[0][1], 0, 0, 0);
;         if (MODE == 0) {
;             const bf16x8 a2 = *(const bf16x8*)(A2 + 16 * s), b20 = *(const bf16x8*)(B2 + 16 * s), b21 = *(const bf16x8*)(B2 + 32 * LDA + 16 * s);
;             acc[NP - 1][0] = __builtin_amdgcn_mfma_f32_32x32x16_bf16(a2, b20, acc[NP - 1][0], 0, 0, 0);
;             acc[NP - 1][1] = __builtin_amdgcn_mfma_f32_32x32x16_bf16(a2, b21, acc[NP - 1][1], 0, 0, 0);
;         }
.LBB0_50:
	s_and_b32 s23, s21, 0xffffffe0
	v_readfirstlane_b32 s0, v216
	s_add_i32 s23, s23, 0x8000
	s_ashr_i32 s24, s0, 6
	v_or_b32_e32 v0, s23, v70
	s_lshl_b32 s0, s24, 7
	v_ashrrev_i32_e32 v1, 31, v0
	v_lshlrev_b64 v[0:1], 12, v[0:1]
	s_ashr_i32 s1, s0, 31
	s_and_b32 s25, s20, 0x3c0
	v_lshl_add_u64 v[0:1], s[76:77], 0, v[0:1]
	s_lshl_b64 s[0:1], s[0:1], 1
	v_lshl_add_u64 v[0:1], v[0:1], 0, s[0:1]
	v_or_b32_e32 v116, s25, v70
	v_lshl_add_u64 v[66:67], v[0:1], 0, v[180:181]
	v_lshlrev_b32_e32 v0, 12, v116
	v_mov_b32_e32 v1, v181
	v_lshl_add_u64 v[0:1], s[78:79], 0, v[0:1]
	v_lshl_add_u64 v[0:1], v[0:1], 0, s[0:1]
	v_lshl_add_u64 v[68:69], v[0:1], 0, v[180:181]
	v_add_co_u32_e32 v64, vcc, s2, v68
	s_nop 1
	v_addc_co_u32_e32 v65, vcc, 0, v69, vcc
	s_add_i32 s22, s22, s84
	s_add_i32 s21, s21, s91
	s_add_i32 s20, s20, s95
	s_cmpk_gt_i32 s22, 0x9f
	global_load_dwordx4 v[132:135], v[66:67], off
	global_load_dwordx4 v[136:139], v[68:69], off
	global_load_dwordx4 v[140:143], v[64:65], off
	global_load_dwordx4 v[144:147], v[66:67], off offset:2048
	global_load_dwordx4 v[148:151], v[68:69], off offset:2048
	global_load_dwordx4 v[152:155], v[64:65], off offset:2048
	global_load_dwordx4 v[156:159], v[66:67], off offset:32
	global_load_dwordx4 v[160:163], v[68:69], off offset:32
	global_load_dwordx4 v[164:167], v[64:65], off offset:32
	global_load_dwordx4 v[168:171], v[66:67], off offset:2080
	global_load_dwordx4 v[172:175], v[68:69], off offset:2080
	global_load_dwordx4 v[176:179], v[64:65], off offset:2080
	global_load_dwordx4 v[188:191], v[66:67], off offset:64
	global_load_dwordx4 v[192:195], v[68:69], off offset:64
	global_load_dwordx4 v[196:199], v[64:65], off offset:64
	global_load_dwordx4 v[200:203], v[66:67], off offset:2112
	global_load_dwordx4 v[204:207], v[68:69], off offset:2112
	global_load_dwordx4 v[208:211], v[64:65], off offset:2112
	global_load_dwordx4 v[220:223], v[66:67], off offset:96
	global_load_dwordx4 v[224:227], v[68:69], off offset:96
	global_load_dwordx4 v[228:231], v[64:65], off offset:96
	global_load_dwordx4 v[232:235], v[66:67], off offset:2144
	global_load_dwordx4 v[236:239], v[68:69], off offset:2144
	global_load_dwordx4 v[240:243], v[64:65], off offset:2144
	s_waitcnt vmcnt(21)
	v_mfma_f32_32x32x16_bf16 v[48:63], v[132:135], v[136:139], 0
	v_mfma_f32_32x32x16_bf16 v[32:47], v[132:135], v[140:143], 0
	global_load_dwordx4 v[132:135], v[66:67], off offset:128
	global_load_dwordx4 v[136:139], v[68:69], off offset:128
	global_load_dwordx4 v[140:143], v[64:65], off offset:128
	s_waitcnt vmcnt(21)
	v_mfma_f32_32x32x16_bf16 v[16:31], v[144:147], v[148:151], 0
	v_mfma_f32_32x32x16_bf16 v[0:15], v[144:147], v[152:155], 0
	global_load_dwordx4 v[144:147], v[66:67], off offset:2176
	global_load_dwordx4 v[148:151], v[68:69], off offset:2176
	global_load_dwordx4 v[152:155], v[64:65], off offset:2176
	s_waitcnt vmcnt(21)
	v_mfma_f32_32x32x16_bf16 v[48:63], v[156:159], v[160:163], v[48:63]
	v_mfma_f32_32x32x16_bf16 v[32:47], v[156:159], v[164:167], v[32:47]
	global_load_dwordx4 v[156:159], v[66:67], off offset:160
	global_load_dwordx4 v[160:163], v[68:69], off offset:160
	global_load_dwordx4 v[164:167], v[64:65], off offset:160
	s_waitcnt vmcnt(21)
	v_mfma_f32_32x32x16_bf16 v[16:31], v[168:171], v[172:175], v[16:31]
	v_mfma_f32_32x32x16_bf16 v[0:15], v[168:171], v[176:179], v[0:15]
	global_load_dwordx4 v[168:171], v[66:67], off offset:2208
	global_load_dwordx4 v[172:175], v[68:69], off offset:2208
	global_load_dwordx4 v[176:179], v[64:65], off offset:2208
	s_waitcnt vmcnt(21)
	v_mfma_f32_32x32x16_bf16 v[48:63], v[188:191], v[192:195], v[48:63]
	v_mfma_f32_32x32x16_bf16 v[32:47], v[188:191], v[196:199], v[32:47]
	global_load_dwordx4 v[188:191], v[66:67], off offset:192
	global_load_dwordx4 v[192:195], v[68:69], off offset:192
	global_load_dwordx4 v[196:199], v[64:65], off offset:192
	s_waitcnt vmcnt(21)
	v_mfma_f32_32x32x16_bf16 v[16:31], v[200:203], v[204:207], v[16:31]
	v_mfma_f32_32x32x16_bf16 v[0:15], v[200:203], v[208:211], v[0:15]
	global_load_dwordx4 v[200:203], v[66:67], off offset:2240
	global_load_dwordx4 v[204:207], v[68:69], off offset:2240
	global_load_dwordx4 v[208:211], v[64:65], off offset:2240
	s_waitcnt vmcnt(21)
	v_mfma_f32_32x32x16_bf16 v[48:63], v[220:223], v[224:227], v[48:63]
	v_mfma_f32_32x32x16_bf16 v[32:47], v[220:223], v[228:231], v[32:47]
	global_load_dwordx4 v[220:223], v[66:67], off offset:224
	global_load_dwordx4 v[224:227], v[68:69], off offset:224
	global_load_dwordx4 v[228:231], v[64:65], off offset:224
	s_waitcnt vmcnt(21)
	v_mfma_f32_32x32x16_bf16 v[16:31], v[232:235], v[236:239], v[16:31]
	v_mfma_f32_32x32x16_bf16 v[0:15], v[232:235], v[240:243], v[0:15]
	global_load_dwordx4 v[232:235], v[66:67], off offset:2272
	global_load_dwordx4 v[236:239], v[68:69], off offset:2272
	global_load_dwordx4 v[240:243], v[64:65], off offset:2272
	s_waitcnt vmcnt(21)
	v_mfma_f32_32x32x16_bf16 v[48:63], v[132:135], v[136:139], v[48:63]
	v_mfma_f32_32x32x16_bf16 v[32:47], v[132:135], v[140:143], v[32:47]
	s_waitcnt vmcnt(18)
	v_mfma_f32_32x32x16_bf16 v[16:31], v[144:147], v[148:151], v[16:31]
	v_mfma_f32_32x32x16_bf16 v[0:15], v[144:147], v[152:155], v[0:15]
	s_waitcnt vmcnt(15)
	v_mfma_f32_32x32x16_bf16 v[48:63], v[156:159], v[160:163], v[48:63]
	v_mfma_f32_32x32x16_bf16 v[32:47], v[156:159], v[164:167], v[32:47]
	s_waitcnt vmcnt(12)
	v_mfma_f32_32x32x16_bf16 v[16:31], v[168:171], v[172:175], v[16:31]
	v_mfma_f32_32x32x16_bf16 v[0:15], v[168:171], v[176:179], v[0:15]
	s_waitcnt vmcnt(9)
	v_mfma_f32_32x32x16_bf16 v[48:63], v[188:191], v[192:195], v[48:63]
	v_mfma_f32_32x32x16_bf16 v[32:47], v[188:191], v[196:199], v[32:47]
	s_waitcnt vmcnt(6)
; #define LAS __attribute__((address_space(3)))
; __device__ __forceinline__ unsigned pk2(float lo, float hi) { unsigned r; asm("v_cvt_pk_bf16_f32 %0, %1, %2" : "=v"(r) : "v"(lo), "v"(hi)); return r; }
; __device__ __forceinline__ float bf1(bf16_t u) { return __uint_as_float(((unsigned)u) << 16); }
; template <int MODE  >
; __device__ __forceinline__ void mini_tile(const Args& a, LAS unsigned char* lds, int tile, int tid) {
;     ...
;     for (int s = 0; s < 8; ++s) {
;         const bf16x8 a1 = *(const bf16x8*)(A1 + 16 * s), b10 = *(const bf16x8*)(B1 + 16 * s), b11 = *(const bf16x8*)(B1 + 32 * LDA + 16 * s);
;         acc[0][0] = __builtin_amdgcn_mfma_f32_32x32x16_bf16(a1, b10, acc[0][0], 0, 0, 0);
;         acc[0][1] = __builtin_amdgcn_mfma_f32_32x32x16_bf16(a1, b11, acc[0][1], 0, 0, 0);
;         if (MODE == 0) {
;             const bf16x8 a2 = *(const bf16x8*)(A2 + 16 * s), b20 = *(const bf16x8*)(B2 + 16 * s), b21 = *(const bf16x8*)(B2 + 32 * LDA + 16 * s);
;             acc[NP - 1][0] = __builtin_amdgcn_mfma_f32_32x32x16_bf16(a2, b20, acc[NP - 1][0], 0, 0, 0);
;             acc[NP - 1][1] = __builtin_amdgcn_mfma_f32_32x32x16_bf16(a2, b21, acc[NP - 1][1], 0, 0, 0);
;         }
;     }
;     LAS float* red = (LAS float*)lds;
; #pragma unroll
;     for (int p = 0; p < NP; ++p)
; #pragma unroll
;         for (int c = 0; c < 2; ++c)
; #pragma unroll
;             for (int i = 0; i < 16; ++i) red[((((wave * NP + p) * 2 + c) * 16 + i) << 6) + lane] = acc[p][c][i];
;     __syncthreads();
; #pragma unroll
;     for (int j = 0; j < 4; ++j) {
;         const int e = tid + 512 * j, c = e >> 10, i = (e >> 6) & 15, l = e & 63;
;         float s1 = 0.f, s2 = 0.f;
; #pragma unroll
;         for (int w = 0; w < 8; ++w) { s1 += red[((((w * NP + 0) * 2 + c) * 16 + i) << 6) + l]; if (MODE == 0) s2 += red[((((w * NP + NP - 1) * 2 + c) * 16 + i) << 6) + l]; }
;         const int row = R0 + 8 * (i >> 2) + 4 * (l >> 5) + (i & 3), col = C0 + 32 * c + (l & 31);
;         if (MODE == 0) {
;             const size_t o = (size_t)row * DM + col;
;             const float m = bf1(PA[6 * (size_t)MPAD * DM + o]) * s1 + bf1(PA[7 * (size_t)MPAD * DM + o]) * s2;
;             ((bf16_t*)(a.ws + WS_MM))[o] = (bf16_t)(pk2(m, m) & 0xffffu);
	v_mfma_f32_32x32x16_bf16 v[16:31], v[200:203], v[204:207], v[16:31]
	v_mfma_f32_32x32x16_bf16 v[0:15], v[200:203], v[208:211], v[0:15]
	s_waitcnt vmcnt(3)
	v_mfma_f32_32x32x16_bf16 v[48:63], v[220:223], v[224:227], v[48:63]
	v_mfma_f32_32x32x16_bf16 v[32:47], v[220:223], v[228:231], v[32:47]
	s_waitcnt vmcnt(0)
	v_mfma_f32_32x32x16_bf16 v[16:31], v[232:235], v[236:239], v[16:31]
	v_mfma_f32_32x32x16_bf16 v[0:15], v[232:235], v[240:243], v[0:15]
	v_lshl_add_u32 v64, s24, 14, v71
	s_nop 11
	ds_write2st64_b32 v64, v48, v49 offset1:1
	ds_write2st64_b32 v64, v50, v51 offset0:2 offset1:3
	ds_write2st64_b32 v64, v52, v53 offset0:4 offset1:5
	ds_write2st64_b32 v64, v54, v55 offset0:6 offset1:7
	ds_write2st64_b32 v64, v56, v57 offset0:8 offset1:9
	ds_write2st64_b32 v64, v58, v59 offset0:10 offset1:11
	ds_write2st64_b32 v64, v60, v61 offset0:12 offset1:13
	ds_write2st64_b32 v64, v62, v63 offset0:14 offset1:15
	ds_write2st64_b32 v64, v32, v33 offset0:16 offset1:17
	ds_write2st64_b32 v64, v34, v35 offset0:18 offset1:19
	ds_write2st64_b32 v64, v36, v37 offset0:20 offset1:21
	ds_write2st64_b32 v64, v38, v39 offset0:22 offset1:23
	ds_write2st64_b32 v64, v40, v41 offset0:24 offset1:25
	ds_write2st64_b32 v64, v42, v43 offset0:26 offset1:27
	ds_write2st64_b32 v64, v44, v45 offset0:28 offset1:29
	ds_write2st64_b32 v64, v46, v47 offset0:30 offset1:31
	ds_write2st64_b32 v64, v16, v17 offset0:32 offset1:33
	ds_write2st64_b32 v64, v18, v19 offset0:34 offset1:35
	ds_write2st64_b32 v64, v20, v21 offset0:36 offset1:37
	ds_write2st64_b32 v64, v22, v23 offset0:38 offset1:39
	ds_write2st64_b32 v64, v24, v25 offset0:40 offset1:41
	ds_write2st64_b32 v64, v26, v27 offset0:42 offset1:43
	ds_write2st64_b32 v64, v28, v29 offset0:44 offset1:45
	ds_write2st64_b32 v64, v30, v31 offset0:46 offset1:47
	ds_write2st64_b32 v64, v0, v1 offset0:48 offset1:49
	ds_write2st64_b32 v64, v2, v3 offset0:50 offset1:51
	ds_write2st64_b32 v64, v4, v5 offset0:52 offset1:53
	ds_write2st64_b32 v64, v6, v7 offset0:54 offset1:55
	ds_write2st64_b32 v64, v8, v9 offset0:56 offset1:57
	ds_write2st64_b32 v64, v10, v11 offset0:58 offset1:59
	ds_write2st64_b32 v64, v12, v13 offset0:60 offset1:61
	ds_write2st64_b32 v64, v14, v15 offset0:62 offset1:63
	s_waitcnt lgkmcnt(0)
	s_barrier
	ds_read2st64_b32 v[0:1], v72 offset1:32
	s_waitcnt lgkmcnt(0)
	v_add_f32_e32 v2, 0, v0
	v_add_f32_e32 v3, 0, v1
	ds_read2st64_b32 v[0:1], v72 offset0:64 offset1:96
	s_waitcnt lgkmcnt(0)
	v_add_f32_e32 v2, v2, v0
	v_add_f32_e32 v3, v3, v1
	ds_read2st64_b32 v[0:1], v72 offset0:128 offset1:160
	s_waitcnt lgkmcnt(0)
	v_add_f32_e32 v2, v2, v0
	v_add_f32_e32 v3, v3, v1
	ds_read2st64_b32 v[0:1], v72 offset0:192 offset1:224
	s_waitcnt lgkmcnt(0)
	v_add_f32_e32 v0, v2, v0
	ds_read_b32 v2, v100
	v_add_f32_e32 v1, v3, v1
	s_waitcnt lgkmcnt(0)
	v_add_f32_e32 v0, v0, v2
	ds_read_b32 v2, v73
	s_waitcnt lgkmcnt(0)
	v_add_f32_e32 v1, v1, v2
	ds_read_b32 v2, v101
	s_waitcnt lgkmcnt(0)
	v_add_f32_e32 v0, v0, v2
	ds_read_b32 v2, v74
	s_waitcnt lgkmcnt(0)
	v_add_f32_e32 v1, v1, v2
	ds_read_b32 v2, v102
	s_waitcnt lgkmcnt(0)
	v_add_f32_e32 v0, v0, v2
	ds_read_b32 v2, v75
	s_waitcnt lgkmcnt(0)
	v_add_f32_e32 v1, v1, v2
	ds_read_b32 v2, v103
	s_waitcnt lgkmcnt(0)
	v_add_f32_e32 v6, v0, v2
	ds_read_b32 v0, v76
	v_add_u32_e32 v2, v116, v78
	v_ashrrev_i32_e32 v3, 31, v2
	s_waitcnt lgkmcnt(0)
	v_add_f32_e32 v7, v1, v0
	v_or_b32_e32 v0, s23, v77
	v_ashrrev_i32_e32 v1, 31, v0
	v_lshlrev_b64 v[0:1], 10, v[0:1]
	v_lshl_add_u64 v[0:1], v[0:1], 0, v[2:3]
	v_lshlrev_b64 v[0:1], 1, v[0:1]
	v_lshl_add_u64 v[2:3], s[74:75], 0, v[0:1]
	v_add_co_u32_e32 v4, vcc, s3, v2
	v_lshl_add_u64 v[0:1], s[88:89], 0, v[0:1]
	s_nop 0
	v_addc_co_u32_e32 v5, vcc, 0, v3, vcc
	v_add_co_u32_e32 v2, vcc, s26, v2
	global_load_ushort v4, v[4:5], off
	s_nop 0
	v_addc_co_u32_e32 v3, vcc, 0, v3, vcc
	global_load_ushort v2, v[2:3], off
	s_waitcnt vmcnt(1)
	v_lshlrev_b32_e32 v4, 16, v4
	s_waitcnt vmcnt(0)
	v_lshlrev_b32_e32 v2, 16, v2
	v_mul_f32_e32 v2, v7, v2
	v_fmac_f32_e32 v2, v6, v4
	v_cvt_pk_bf16_f32 v2, v2, v2
	global_store_short v[0:1], v2, off
	ds_read2st64_b32 v[0:1], v79 offset1:32
	s_waitcnt lgkmcnt(0)
	v_add_f32_e32 v2, 0, v0
	v_add_f32_e32 v3, 0, v1
	ds_read2st64_b32 v[0:1], v79 offset0:64 offset1:96
	s_waitcnt lgkmcnt(0)
	v_add_f32_e32 v2, v2, v0
	v_add_f32_e32 v3, v3, v1
	ds_read2st64_b32 v[0:1], v79 offset0:128 offset1:160
	s_waitcnt lgkmcnt(0)
	v_add_f32_e32 v2, v2, v0
	v_add_f32_e32 v3, v3, v1
	ds_read2st64_b32 v[0:1], v79 offset0:192 offset1:224
	s_waitcnt lgkmcnt(0)
	v_add_f32_e32 v0, v2, v0
	ds_read_b32 v2, v104
	v_add_f32_e32 v1, v3, v1
	s_waitcnt lgkmcnt(0)
	v_add_f32_e32 v0, v0, v2
	ds_read_b32 v2, v80
	s_waitcnt lgkmcnt(0)
	v_add_f32_e32 v1, v1, v2
	ds_read_b32 v2, v105
	s_waitcnt lgkmcnt(0)
; __device__ __forceinline__ unsigned pk2(float lo, float hi) { unsigned r; asm("v_cvt_pk_bf16_f32 %0, %1, %2" : "=v"(r) : "v"(lo), "v"(hi)); return r; }
; __device__ __forceinline__ float bf1(bf16_t u) { return __uint_as_float(((unsigned)u) << 16); }
; template <int MODE  >
; __device__ __forceinline__ void mini_tile(const Args& a, LAS unsigned char* lds, int tile, int tid) {
;     ...
; #pragma unroll
;     for (int j = 0; j < 4; ++j) {
;         const int e = tid + 512 * j, c = e >> 10, i = (e >> 6) & 15, l = e & 63;
;         float s1 = 0.f, s2 = 0.f;
; #pragma unroll
;         for (int w = 0; w < 8; ++w) { s1 += red[((((w * NP + 0) * 2 + c) * 16 + i) << 6) + l]; if (MODE == 0) s2 += red[((((w * NP + NP - 1) * 2 + c) * 16 + i) << 6) + l]; }
;         const int row = R0 + 8 * (i >> 2) + 4 * (l >> 5) + (i & 3), col = C0 + 32 * c + (l & 31);
;         if (MODE == 0) {
;             const size_t o = (size_t)row * DM + col;
;             const float m = bf1(PA[6 * (size_t)MPAD * DM + o]) * s1 + bf1(PA[7 * (size_t)MPAD * DM + o]) * s2;
;             ((bf16_t*)(a.ws + WS_MM))[o] = (bf16_t)(pk2(m, m) & 0xffffu);
;         } else {
;             if (row < MP) { const int b = row / TP, t = row - b * TP; if (t >= NMETA) { const size_t o = ((size_t)b * SEQ + (t - NMETA)) * DM + col; a.out[O_YP + o] = a.xp[o] + s1; } }
;             else if (row < MV) { const size_t o = (size_t)(row - MP) * DM + col; a.out[O_YS + o] = a.xs[o] + s1; }
;         }
;     }
;     __syncthreads();
	v_add_f32_e32 v0, v0, v2
	ds_read_b32 v2, v81
	s_waitcnt lgkmcnt(0)
	v_add_f32_e32 v1, v1, v2
	ds_read_b32 v2, v106
	s_waitcnt lgkmcnt(0)
	v_add_f32_e32 v0, v0, v2
	ds_read_b32 v2, v82
	s_waitcnt lgkmcnt(0)
	v_add_f32_e32 v1, v1, v2
	ds_read_b32 v2, v107
	s_waitcnt lgkmcnt(0)
	v_add_f32_e32 v6, v0, v2
	ds_read_b32 v0, v83
	v_add_u32_e32 v2, v116, v85
	v_ashrrev_i32_e32 v3, 31, v2
	s_waitcnt lgkmcnt(0)
	v_add_f32_e32 v7, v1, v0
	v_or_b32_e32 v0, s23, v84
	v_ashrrev_i32_e32 v1, 31, v0
	v_lshlrev_b64 v[0:1], 10, v[0:1]
	v_lshl_add_u64 v[0:1], v[0:1], 0, v[2:3]
	v_lshlrev_b64 v[0:1], 1, v[0:1]
	v_lshl_add_u64 v[2:3], s[74:75], 0, v[0:1]
	v_add_co_u32_e32 v4, vcc, s3, v2
	v_lshl_add_u64 v[0:1], s[88:89], 0, v[0:1]
	s_nop 0
	v_addc_co_u32_e32 v5, vcc, 0, v3, vcc
	v_add_co_u32_e32 v2, vcc, s26, v2
	global_load_ushort v4, v[4:5], off
	s_nop 0
	v_addc_co_u32_e32 v3, vcc, 0, v3, vcc
	global_load_ushort v2, v[2:3], off
	s_waitcnt vmcnt(1)
	v_lshlrev_b32_e32 v4, 16, v4
	s_waitcnt vmcnt(0)
	v_lshlrev_b32_e32 v2, 16, v2
	v_mul_f32_e32 v2, v7, v2
	v_fmac_f32_e32 v2, v6, v4
	v_cvt_pk_bf16_f32 v2, v2, v2
	global_store_short v[0:1], v2, off
	ds_read2st64_b32 v[0:1], v86 offset1:32
	s_waitcnt lgkmcnt(0)
	v_add_f32_e32 v2, 0, v0
	v_add_f32_e32 v3, 0, v1
	ds_read2st64_b32 v[0:1], v86 offset0:64 offset1:96
	s_waitcnt lgkmcnt(0)
	v_add_f32_e32 v2, v2, v0
	v_add_f32_e32 v3, v3, v1
	ds_read2st64_b32 v[0:1], v86 offset0:128 offset1:160
	s_waitcnt lgkmcnt(0)
	v_add_f32_e32 v2, v2, v0
	v_add_f32_e32 v3, v3, v1
	ds_read2st64_b32 v[0:1], v86 offset0:192 offset1:224
	s_waitcnt lgkmcnt(0)
	v_add_f32_e32 v0, v2, v0
	ds_read_b32 v2, v108
	v_add_f32_e32 v1, v3, v1
	s_waitcnt lgkmcnt(0)
	v_add_f32_e32 v0, v0, v2
	ds_read_b32 v2, v87
	s_waitcnt lgkmcnt(0)
	v_add_f32_e32 v1, v1, v2
	ds_read_b32 v2, v109
	s_waitcnt lgkmcnt(0)
	v_add_f32_e32 v0, v0, v2
	ds_read_b32 v2, v88
	s_waitcnt lgkmcnt(0)
	v_add_f32_e32 v1, v1, v2
	ds_read_b32 v2, v110
	s_waitcnt lgkmcnt(0)
	v_add_f32_e32 v0, v0, v2
	ds_read_b32 v2, v89
	s_waitcnt lgkmcnt(0)
	v_add_f32_e32 v1, v1, v2
	ds_read_b32 v2, v111
	s_waitcnt lgkmcnt(0)
	v_add_f32_e32 v6, v0, v2
	ds_read_b32 v0, v90
	v_add_u32_e32 v2, v116, v92
	v_ashrrev_i32_e32 v3, 31, v2
	s_waitcnt lgkmcnt(0)
	v_add_f32_e32 v7, v1, v0
	v_or_b32_e32 v0, s23, v91
	v_ashrrev_i32_e32 v1, 31, v0
	v_lshlrev_b64 v[0:1], 10, v[0:1]
	v_lshl_add_u64 v[0:1], v[0:1], 0, v[2:3]
	v_lshlrev_b64 v[0:1], 1, v[0:1]
	v_lshl_add_u64 v[2:3], s[74:75], 0, v[0:1]
	v_add_co_u32_e32 v4, vcc, s3, v2
	v_lshl_add_u64 v[0:1], s[88:89], 0, v[0:1]
	s_nop 0
	v_addc_co_u32_e32 v5, vcc, 0, v3, vcc
	v_add_co_u32_e32 v2, vcc, s26, v2
	global_load_ushort v4, v[4:5], off
	s_nop 0
	v_addc_co_u32_e32 v3, vcc, 0, v3, vcc
	global_load_ushort v2, v[2:3], off
	s_waitcnt vmcnt(1)
	v_lshlrev_b32_e32 v4, 16, v4
	s_waitcnt vmcnt(0)
	v_lshlrev_b32_e32 v2, 16, v2
	v_mul_f32_e32 v2, v7, v2
	v_fmac_f32_e32 v2, v6, v4
	v_cvt_pk_bf16_f32 v2, v2, v2
	global_store_short v[0:1], v2, off
	ds_read2st64_b32 v[0:1], v93 offset1:32
	s_waitcnt lgkmcnt(0)
	v_add_f32_e32 v2, 0, v0
	v_add_f32_e32 v3, 0, v1
	ds_read2st64_b32 v[0:1], v93 offset0:64 offset1:96
	s_waitcnt lgkmcnt(0)
	v_add_f32_e32 v2, v2, v0
	v_add_f32_e32 v3, v3, v1
	ds_read2st64_b32 v[0:1], v93 offset0:128 offset1:160
	s_waitcnt lgkmcnt(0)
	v_add_f32_e32 v2, v2, v0
	v_add_f32_e32 v3, v3, v1
	ds_read2st64_b32 v[0:1], v93 offset0:192 offset1:224
	s_waitcnt lgkmcnt(0)
	v_add_f32_e32 v0, v2, v0
	ds_read_b32 v2, v112
	v_add_f32_e32 v1, v3, v1
	s_waitcnt lgkmcnt(0)
	v_add_f32_e32 v0, v0, v2
	ds_read_b32 v2, v94
	s_waitcnt lgkmcnt(0)
	v_add_f32_e32 v1, v1, v2
	ds_read_b32 v2, v113
	s_waitcnt lgkmcnt(0)
	v_add_f32_e32 v0, v0, v2
	ds_read_b32 v2, v95
	s_waitcnt lgkmcnt(0)
	v_add_f32_e32 v1, v1, v2
	ds_read_b32 v2, v114
	s_waitcnt lgkmcnt(0)
	v_add_f32_e32 v0, v0, v2
	ds_read_b32 v2, v96
	s_waitcnt lgkmcnt(0)
	v_add_f32_e32 v1, v1, v2
	ds_read_b32 v2, v115
	s_waitcnt lgkmcnt(0)
	v_add_f32_e32 v6, v0, v2
	ds_read_b32 v0, v97
	v_add_u32_e32 v2, v116, v99
	v_ashrrev_i32_e32 v3, 31, v2
	s_waitcnt lgkmcnt(0)
	v_add_f32_e32 v7, v1, v0
	v_or_b32_e32 v0, s23, v98
	v_ashrrev_i32_e32 v1, 31, v0
	v_lshlrev_b64 v[0:1], 10, v[0:1]
	v_lshl_add_u64 v[0:1], v[0:1], 0, v[2:3]
	v_lshlrev_b64 v[0:1], 1, v[0:1]
	v_lshl_add_u64 v[2:3], s[74:75], 0, v[0:1]
	v_add_co_u32_e32 v4, vcc, s3, v2
	v_lshl_add_u64 v[0:1], s[88:89], 0, v[0:1]
	s_nop 0
	v_addc_co_u32_e32 v5, vcc, 0, v3, vcc
	v_add_co_u32_e32 v2, vcc, s26, v2
	global_load_ushort v4, v[4:5], off
	s_nop 0
	v_addc_co_u32_e32 v3, vcc, 0, v3, vcc
	global_load_ushort v2, v[2:3], off
	s_waitcnt vmcnt(1)
	v_lshlrev_b32_e32 v4, 16, v4
	s_waitcnt vmcnt(0)
	v_lshlrev_b32_e32 v2, 16, v2
	v_mul_f32_e32 v2, v7, v2
	v_fmac_f32_e32 v2, v6, v4
	v_cvt_pk_bf16_f32 v2, v2, v2
	global_store_short v[0:1], v2, off
	s_barrier
	s_cbranch_scc0 .LBB0_50

; #define PG8_STAGE(bufoff, gbase) do { _Pragma("unroll") for (int _i = 0; _i < 2; ++_i) \
;         __builtin_amdgcn_global_load_lds((const unsigned*)((const char*)(gbase) + voffA[_i]), (LAS unsigned*)(lds + (bufoff) + ldsw + _i * 8192), 16, 0, 0); } while (0)
; #define PG8_STAGEB(bufoff, gbase) do { _Pragma("unroll") for (int _i = 0; _i < 2; ++_i) \
;         __builtin_amdgcn_global_load_lds((const unsigned*)((const char*)(gbase) + voffB[_i]), (LAS unsigned*)(lds + (bufoff) + ldsw + _i * 8192), 16, 0, 0); } while (0)
; template <class Epi, bool TWO, bool PERM, bool BIAS = false>
; __device__ __forceinline__ void gemm_phase(LAS unsigned char* lds, const Gemm g, const StaticOrder& S, const Epi& E, const int tid) {
;     const int wid = __builtin_amdgcn_readfirstlane(tid >> 6), lane = tid & 63, wr = wid >> 2, wc = wid & 3, fr = lane & 15, fq = lane >> 4;
;     const int K = g.K, nt = g.nt;
;     unsigned voffA[2], voffB[2];
; #pragma unroll
;     for (int i = 0; i < 2; ++i) { int R, C; stage_rc(tid * 16 + i * 8192, R, C); const int Rb = PERM ? ((R & ~31) + perm32(R & 31)) : R;
;         voffA[i] = (unsigned)(R * K + C) * 2u; voffB[i] = (unsigned)(Rb * K + C) * 2u; }
;     const size_t kstep = (size_t)(BK * 2);
;     const size_t hstep = (size_t)HALF * K * 2;
;     const size_t tstep = 2 * hstep;
;     const unsigned ldsw = (unsigned)wid * 1024u;
;     const int aoff = lds_byte(wr * 64 + fr, fq * 8), boff = lds_byte(wc * 32 + fr, fq * 8);
;     ...
;     Unit cur, nxt; int ui = 0;
;     if (!S.next(0, cur)) return;
;     f32x4 acc[2][2][4][2], binit[2][2];
; #pragma unroll
;     for (int b = 0; b < 2; ++b)
; #pragma unroll
;         for (int n = 0; n < 2; ++n) binit[b][n] = (f32x4){0.f, 0.f, 0.f, 0.f};
;     if constexpr (BIAS) E.load_bias(cur, wc, fq, binit);
; #pragma unroll
;     for (int a = 0; a < 2; ++a)
; #pragma unroll
;         for (int b = 0; b < 2; ++b)
; #pragma unroll
;             for (int m = 0; m < 4; ++m)
; #pragma unroll
;                 for (int n = 0; n < 2; ++n) acc[a][b][m][n] = binit[b][n];
;     bf16x8 At[4][2], B0[2][2], B1[2][2];
;     const char* cA = (const char*)g.A + (size_t)cur.pm * tstep; const char* cB = (const char*)g.Bt + (size_t)cur.pn * tstep;
;     PG8_STAGEB(PG8_SB(0, 0), cB); PG8_STAGEB(PG8_SB(0, 1), cB + hstep); PG8_STAGE(PG8_SA(0, 0), cA); PG8_STAGE(PG8_SA(0, 1), cA + hstep);
;     if (wr == 1) PG8_BAR;
.LBB0_595:
	s_and_b64 vcc, exec, s[0:1]
	s_cbranch_vccz .LBB0_1082
	s_cmp_lg_u32 s24, 1
	s_mov_b64 s[0:1], -1
	s_cbranch_scc0 .LBB0_693
	s_branch .LBB0_665
.Lsb_gemm6:
	v_readlane_b32 s0, v252, 6
	v_readlane_b32 s1, v252, 7
	s_andn2_b64 vcc, exec, s[0:1]
	v_readfirstlane_b32 s20, v216
	s_cbranch_vccnz .LBB0_692
	s_waitcnt vmcnt(0)
	v_lshlrev_b32_e32 v3, 4, v216
	v_add_u32_e32 v1, 0x2000, v3
	v_ashrrev_i32_e32 v0, 31, v1
	v_lshrrev_b32_e32 v0, 22, v0
	v_add_u32_e32 v0, v1, v0
	v_ashrrev_i32_e32 v0, 10, v0
	v_mul_i32_i24_e32 v2, 0x400, v0
	v_sub_u32_e32 v1, v1, v2
	v_lshrrev_b32_e32 v2, 4, v1
	v_bitop3_b32 v2, v2, v1, 32 bitop3:0x6c
	v_ashrrev_i32_e32 v1, 31, v2
	v_lshrrev_b32_e32 v1, 26, v1
	v_add_u32_e32 v4, v2, v1
	v_lshlrev_b32_e32 v5, 3, v0
	v_ashrrev_i32_e32 v1, 6, v4
	v_and_b32_e32 v5, -16, v5
	v_add_u32_e32 v5, v1, v5
	v_and_b32_e32 v6, 3, v1
	s_mov_b32 s0, 0x1fffe0
	v_lshrrev_b32_e32 v7, 2, v5
	v_lshlrev_b32_e32 v8, 1, v5
	v_and_b32_e32 v4, 0xc0, v4
	v_and_or_b32 v6, v5, s0, v6
	v_and_b32_e32 v7, 4, v7
	v_and_b32_e32 v8, 24, v8
	v_sub_u32_e32 v2, v2, v4
	v_or3_b32 v6, v6, v7, v8
	v_lshlrev_b32_e32 v7, 5, v0
	v_ashrrev_i16_sdwa v2, v214, sext(v2) dst_sel:DWORD dst_unused:UNUSED_PAD src0_sel:DWORD src1_sel:BYTE_0
	v_and_b32_e32 v7, 32, v7
	v_bfe_i32 v2, v2, 0, 16
	v_add_lshl_u32 v4, v7, v2, 1
	v_lshl_add_u32 v160, v6, 11, v4
	v_lshl_add_u32 v162, v5, 11, v4
	v_bfe_i32 v4, v216, 27, 1
	v_lshrrev_b32_e32 v4, 22, v4
	v_add_u32_e32 v4, v3, v4
	v_and_b32_e32 v4, 0xfffffc00, v4
	v_sub_u32_e32 v3, v3, v4
	v_lshrrev_b32_e32 v4, 4, v3
	v_bitop3_b32 v5, v4, v3, 32 bitop3:0x6c
	v_ashrrev_i32_e32 v4, 31, v216
	v_lshrrev_b32_e32 v4, 26, v4
	v_ashrrev_i32_e32 v3, 31, v5
	v_add_u32_e32 v4, v216, v4
	v_lshrrev_b32_e32 v3, 26, v3
	v_ashrrev_i32_e32 v4, 6, v4
	v_add_u32_e32 v6, v5, v3
	v_lshlrev_b32_e32 v7, 3, v4
	v_ashrrev_i32_e32 v3, 6, v6
	v_and_b32_e32 v7, -16, v7
	v_add_u32_e32 v7, v3, v7
	v_and_b32_e32 v8, 3, v3
	v_lshrrev_b32_e32 v9, 2, v7
	v_lshlrev_b32_e32 v10, 1, v7
	v_and_b32_e32 v6, 0xc0, v6
	v_and_or_b32 v8, v7, s0, v8
	v_and_b32_e32 v9, 4, v9
	v_and_b32_e32 v10, 24, v10
	v_sub_u32_e32 v5, v5, v6
	s_ashr_i32 s21, s20, 6
	v_or3_b32 v8, v8, v9, v10
	v_lshlrev_b32_e32 v9, 5, v4
	v_ashrrev_i16_sdwa v5, v214, sext(v5) dst_sel:DWORD dst_unused:UNUSED_PAD src0_sel:DWORD src1_sel:BYTE_0
	s_lshl_b32 s8, s21, 10
	v_and_b32_e32 v9, 32, v9
	v_bfe_i32 v5, v5, 0, 16
	v_add_lshl_u32 v6, v9, v5, 1
	s_add_i32 s26, s8, 0
	v_readlane_b32 s0, v254, 25
	v_lshl_add_u32 v164, v8, 11, v6
	s_add_i32 m0, s26, 0x10000
	v_readlane_b32 s1, v254, 26
	v_lshl_add_u32 v166, v7, 11, v6
	s_add_i32 s27, s26, 0x2000
	s_add_i32 s28, s26, 0x4000
	s_add_i32 s29, s26, 0x6000
	s_ashr_i32 s22, s20, 8
	global_load_lds_dwordx4 v164, s[0:1]
	s_add_i32 m0, s26, 0x12000
	s_nop 0
	global_load_lds_dwordx4 v160, s[0:1]
	v_readlane_b32 s0, v254, 19
	s_add_i32 m0, s26, 0x14000
	v_readlane_b32 s1, v254, 20
	s_nop 4
	global_load_lds_dwordx4 v164, s[0:1]
	s_add_i32 m0, s26, 0x16000
	s_cmp_eq_u32 s22, 1
	global_load_lds_dwordx4 v160, s[0:1]
	v_readlane_b32 s0, v254, 21
	s_mov_b32 m0, s26
	v_readlane_b32 s1, v254, 22
	s_nop 4
	global_load_lds_dwordx4 v166, s[0:1]
	s_mov_b32 m0, s27
	s_nop 0
	global_load_lds_dwordx4 v162, s[0:1]
	v_readlane_b32 s0, v254, 23
	s_mov_b32 m0, s28
	v_readlane_b32 s1, v254, 24
	s_nop 4
	global_load_lds_dwordx4 v166, s[0:1]
	s_mov_b32 m0, s29
	s_nop 0
	global_load_lds_dwordx4 v162, s[0:1]
	s_cselect_b64 s[0:1], -1, 0
	s_cmp_lg_u32 s22, 1
	s_cbranch_scc1 .LBB0_600
	s_barrier

; #define PG8_WAIT_V(n) asm volatile("s_waitcnt vmcnt(" #n ")" ::: "memory")
; #define PG8_BAR __builtin_amdgcn_s_barrier()
; template <class Epi, bool TWO, bool PERM, bool BIAS = false>
; __device__ __forceinline__ void gemm_phase(LAS unsigned char* lds, const Gemm g, const StaticOrder& S, const Epi& E, const int tid) {
;     ...
;     PG8_WAIT_V(0);
;     PG8_BAR;
.LBB0_664:
	s_waitcnt vmcnt(0)
	s_barrier
	s_branch .LBB0_692

; #define LAS __attribute__((address_space(3)))
; template <int MODE  >
; __device__ __forceinline__ void mini_tile(const Args& a, LAS unsigned char* lds, int tile, int tid) {
;     ...
;     for (int s = 0; s < 8; ++s) {
;         const bf16x8 a1 = *(const bf16x8*)(A1 + 16 * s), b10 = *(const bf16x8*)(B1 + 16 * s), b11 = *(const bf16x8*)(B1 + 32 * LDA + 16 * s);
;         acc[0][0] = __builtin_amdgcn_mfma_f32_32x32x16_bf16(a1, b10, acc[0][0], 0, 0, 0);
;         acc[0][1] = __builtin_amdgcn_mfma_f32_32x32x16_bf16(a1, b11, acc[0][1], 0, 0, 0);
;         if (MODE == 0) {
;             const bf16x8 a2 = *(const bf16x8*)(A2 + 16 * s), b20 = *(const bf16x8*)(B2 + 16 * s), b21 = *(const bf16x8*)(B2 + 32 * LDA + 16 * s);
;             acc[NP - 1][0] = __builtin_amdgcn_mfma_f32_32x32x16_bf16(a2, b20, acc[NP - 1][0], 0, 0, 0);
;             acc[NP - 1][1] = __builtin_amdgcn_mfma_f32_32x32x16_bf16(a2, b21, acc[NP - 1][1], 0, 0, 0);
;         }
;     }
;     LAS float* red = (LAS float*)lds;
; #pragma unroll
;     for (int p = 0; p < NP; ++p)
; #pragma unroll
;         for (int c = 0; c < 2; ++c)
; #pragma unroll
;             for (int i = 0; i < 16; ++i) red[((((wave * NP + p) * 2 + c) * 16 + i) << 6) + lane] = acc[p][c][i];
;     __syncthreads();
; #pragma unroll
;     for (int j = 0; j < 4; ++j) {
;         const int e = tid + 512 * j, c = e >> 10, i = (e >> 6) & 15, l = e & 63;
;         float s1 = 0.f, s2 = 0.f;
; #pragma unroll
;         for (int w = 0; w < 8; ++w) { s1 += red[((((w * NP + 0) * 2 + c) * 16 + i) << 6) + l]; if (MODE == 0) s2 += red[((((w * NP + NP - 1) * 2 + c) * 16 + i) << 6) + l]; }
;         const int row = R0 + 8 * (i >> 2) + 4 * (l >> 5) + (i & 3), col = C0 + 32 * c + (l & 31);
;         if (MODE == 0) {
;             const size_t o = (size_t)row * DM + col;
;             const float m = bf1(PA[6 * (size_t)MPAD * DM + o]) * s1 + bf1(PA[7 * (size_t)MPAD * DM + o]) * s2;
;             ((bf16_t*)(a.ws + WS_MM))[o] = (bf16_t)(pk2(m, m) & 0xffffu);
;         } else {
;             if (row < MP) { const int b = row / TP, t = row - b * TP; if (t >= NMETA) { const size_t o = ((size_t)b * SEQ + (t - NMETA)) * DM + col; a.out[O_YP + o] = a.xp[o] + s1; } }
;             else if (row < MV) { const size_t o = (size_t)(row - MP) * DM + col; a.out[O_YS + o] = a.xs[o] + s1; }
.LBB0_669:
	v_readfirstlane_b32 s0, v216
	s_ashr_i32 s0, s0, 6
	s_and_b32 s24, s22, 0xffffffe0
	s_and_b32 s1, s8, 0x3c0
	s_add_i32 s24, s24, 0x8000
	s_lshl_b32 s20, s0, 7
	v_or_b32_e32 v48, s1, v34
	v_readlane_b32 s2, v254, 17
	v_or_b32_e32 v0, s24, v34
	s_ashr_i32 s21, s20, 31
	v_lshlrev_b32_e32 v180, 11, v48
	v_readlane_b32 s3, v254, 18
	v_ashrrev_i32_e32 v1, 31, v0
	s_lshl_b64 s[20:21], s[20:21], 1
	v_lshl_add_u64 v[2:3], s[2:3], 0, v[180:181]
	v_lshlrev_b64 v[0:1], 11, v[0:1]
	v_lshl_add_u64 v[2:3], v[2:3], 0, s[20:21]
	v_mov_b32_e32 v33, v181
	v_lshl_add_u64 v[0:1], s[88:89], 0, v[0:1]
	v_lshl_add_u64 v[64:65], v[2:3], 0, v[32:33]
	s_mov_b32 s1, 0x10000
	v_lshl_add_u64 v[0:1], v[0:1], 0, s[20:21]
	v_add_co_u32_e32 v66, vcc, s1, v64
	v_lshl_add_u64 v[62:63], v[0:1], 0, v[32:33]
	s_nop 0
	v_addc_co_u32_e32 v67, vcc, 0, v65, vcc
	global_load_dwordx4 v[68:71], v[62:63], off
	global_load_dwordx4 v[72:75], v[64:65], off
	global_load_dwordx4 v[76:79], v[66:67], off
	global_load_dwordx4 v[80:83], v[62:63], off offset:32
	global_load_dwordx4 v[84:87], v[64:65], off offset:32
	global_load_dwordx4 v[88:91], v[66:67], off offset:32
	global_load_dwordx4 v[92:95], v[62:63], off offset:64
	global_load_dwordx4 v[96:99], v[64:65], off offset:64
	global_load_dwordx4 v[100:103], v[66:67], off offset:64
	global_load_dwordx4 v[104:107], v[62:63], off offset:96
	global_load_dwordx4 v[108:111], v[64:65], off offset:96
	global_load_dwordx4 v[112:115], v[66:67], off offset:96
	global_load_dwordx4 v[116:119], v[62:63], off offset:128
	global_load_dwordx4 v[120:123], v[64:65], off offset:128
	global_load_dwordx4 v[124:127], v[66:67], off offset:128
	global_load_dwordx4 v[128:131], v[62:63], off offset:160
	global_load_dwordx4 v[132:135], v[64:65], off offset:160
	global_load_dwordx4 v[136:139], v[66:67], off offset:160
	global_load_dwordx4 v[140:143], v[62:63], off offset:192
	global_load_dwordx4 v[144:147], v[64:65], off offset:192
	global_load_dwordx4 v[148:151], v[66:67], off offset:192
	global_load_dwordx4 v[152:155], v[62:63], off offset:224
	global_load_dwordx4 v[156:159], v[64:65], off offset:224
	global_load_dwordx4 v[160:163], v[66:67], off offset:224
	v_lshl_add_u32 v33, s0, 13, v35
	s_waitcnt vmcnt(21)
	v_mfma_f32_32x32x16_bf16 v[16:31], v[68:71], v[72:75], 0
	v_mfma_f32_32x32x16_bf16 v[0:15], v[68:71], v[76:79], 0
	s_waitcnt vmcnt(18)
	v_mfma_f32_32x32x16_bf16 v[16:31], v[80:83], v[84:87], v[16:31]
	v_mfma_f32_32x32x16_bf16 v[0:15], v[80:83], v[88:91], v[0:15]
	s_waitcnt vmcnt(15)
	v_mfma_f32_32x32x16_bf16 v[16:31], v[92:95], v[96:99], v[16:31]
	v_mfma_f32_32x32x16_bf16 v[0:15], v[92:95], v[100:103], v[0:15]
	s_waitcnt vmcnt(12)
	v_mfma_f32_32x32x16_bf16 v[16:31], v[104:107], v[108:111], v[16:31]
	v_mfma_f32_32x32x16_bf16 v[0:15], v[104:107], v[112:115], v[0:15]
	s_waitcnt vmcnt(9)
	v_mfma_f32_32x32x16_bf16 v[16:31], v[116:119], v[120:123], v[16:31]
	v_mfma_f32_32x32x16_bf16 v[0:15], v[116:119], v[124:127], v[0:15]
	s_waitcnt vmcnt(6)
	v_mfma_f32_32x32x16_bf16 v[16:31], v[128:131], v[132:135], v[16:31]
	v_mfma_f32_32x32x16_bf16 v[0:15], v[128:131], v[136:139], v[0:15]
	s_waitcnt vmcnt(3)
	v_mfma_f32_32x32x16_bf16 v[16:31], v[140:143], v[144:147], v[16:31]
	v_mfma_f32_32x32x16_bf16 v[0:15], v[140:143], v[148:151], v[0:15]
	s_waitcnt vmcnt(0)
	v_mfma_f32_32x32x16_bf16 v[16:31], v[152:155], v[156:159], v[16:31]
	v_mfma_f32_32x32x16_bf16 v[0:15], v[152:155], v[160:163], v[0:15]
	s_nop 11
	ds_write2st64_b32 v33, v16, v17 offset1:1
	ds_write2st64_b32 v33, v18, v19 offset0:2 offset1:3
	ds_write2st64_b32 v33, v20, v21 offset0:4 offset1:5
	ds_write2st64_b32 v33, v22, v23 offset0:6 offset1:7
	ds_write2st64_b32 v33, v24, v25 offset0:8 offset1:9
	ds_write2st64_b32 v33, v26, v27 offset0:10 offset1:11
	ds_write2st64_b32 v33, v28, v29 offset0:12 offset1:13
	ds_write2st64_b32 v33, v30, v31 offset0:14 offset1:15
	ds_write2st64_b32 v33, v0, v1 offset0:16 offset1:17
	ds_write2st64_b32 v33, v2, v3 offset0:18 offset1:19
	ds_write2st64_b32 v33, v4, v5 offset0:20 offset1:21
	ds_write2st64_b32 v33, v6, v7 offset0:22 offset1:23
	ds_write2st64_b32 v33, v8, v9 offset0:24 offset1:25
	ds_write2st64_b32 v33, v10, v11 offset0:26 offset1:27
	ds_write2st64_b32 v33, v12, v13 offset0:28 offset1:29
	ds_write2st64_b32 v33, v14, v15 offset0:30 offset1:31
	s_waitcnt lgkmcnt(0)
	s_barrier
	ds_read2st64_b32 v[0:1], v44 offset1:32
	s_waitcnt lgkmcnt(0)
	v_add_f32_e32 v0, 0, v0
	v_add_f32_e32 v2, v0, v1
	ds_read2st64_b32 v[0:1], v44 offset0:64 offset1:96
	s_waitcnt lgkmcnt(0)
	v_add_f32_e32 v0, v2, v0
	v_add_f32_e32 v2, v0, v1
	ds_read2st64_b32 v[0:1], v44 offset0:128 offset1:160
	s_waitcnt lgkmcnt(0)
	v_add_f32_e32 v0, v2, v0
	v_add_f32_e32 v2, v0, v1
	ds_read2st64_b32 v[0:1], v44 offset0:192 offset1:224
	s_waitcnt lgkmcnt(0)
	v_add_f32_e32 v0, v2, v0
	v_add_f32_e32 v4, v0, v1
	v_or_b32_e32 v1, s24, v36
	v_add_u32_e32 v0, v48, v37
	v_cmp_lt_i32_e32 vcc, s82, v1
	s_and_saveexec_b64 s[0:1], vcc
	s_xor_b64 s[0:1], exec, s[0:1]
	s_cbranch_execz .LBB0_671
	v_add_u32_e32 v180, 0xffff7fc0, v1
	v_lshlrev_b64 v[2:3], 10, v[180:181]
	v_ashrrev_i32_e32 v1, 31, v0
	v_lshl_add_u64 v[0:1], v[2:3], 0, v[0:1]
	v_lshlrev_b64 v[0:1], 2, v[0:1]
	v_lshl_add_u64 v[2:3], s[6:7], 0, v[0:1]
	global_load_dword v2, v[2:3], off
	v_readlane_b32 s36, v252, 40
	v_readlane_b32 s50, v252, 54
	v_readlane_b32 s51, v252, 55
	v_readlane_b32 s37, v252, 41
	v_readlane_b32 s38, v252, 42
	v_lshl_add_u64 v[0:1], s[50:51], 0, v[0:1]
	v_add_co_u32_e32 v0, vcc, 0x8000000, v0
	v_readlane_b32 s39, v252, 43
	s_nop 0
	v_addc_co_u32_e32 v1, vcc, 0, v1, vcc
	v_readlane_b32 s40, v252, 44
	v_readlane_b32 s41, v252, 45
	v_readlane_b32 s42, v252, 46
	v_readlane_b32 s43, v252, 47
	v_readlane_b32 s44, v252, 48
	v_readlane_b32 s45, v252, 49
	v_readlane_b32 s46, v252, 50
	v_readlane_b32 s47, v252, 51
	v_readlane_b32 s48, v252, 52
	v_readlane_b32 s49, v252, 53
	s_waitcnt vmcnt(0)
	v_add_f32_e32 v2, v4, v2
	global_store_dword v[0:1], v2, off

; __device__ __forceinline__ unsigned xb_ld(unsigned* p)              { return __hip_atomic_load(p, __ATOMIC_RELAXED, __HIP_MEMORY_SCOPE_AGENT); }
; __device__ __forceinline__ void xcd_barrier_complete(unsigned* bar, unsigned x, unsigned& nloc, unsigned& nx) {
;     ...
;     for (;;) {
;         sum = 0u; cnt = 0u; mine = 0u;
; #pragma unroll
;         for (unsigned j = 0; j < 16; ++j) { const unsigned c = xb_ld(&bar[XB_XCNT(j)]); sum += c; cnt += (c > 0u) ? 1u : 0u; mine = (j == x) ? c : mine; }
;         if (sum == G) break;
;         __builtin_amdgcn_s_sleep(1);
;         if ((++sp & 255u) == 0u) { if (xb_ld(&bar[XB_TMO])) break; if (sp > XB_SPIN_CAP) { atomicAdd(&bar[XB_TMO], 1u); break; } }
;     }
.LBB0_1193:
	v_readlane_b32 s2, v252, 60
	v_readlane_b32 s3, v252, 61
	s_mov_b64 s[20:21], -1
	s_mov_b64 s[22:23], -1
	s_waitcnt lgkmcnt(0)
	s_nop 1
	global_load_dword v0, v181, s[2:3] sc1
	v_readlane_b32 s2, v252, 62
	v_readlane_b32 s3, v252, 63
	s_nop 4
	global_load_dword v1, v181, s[2:3] sc1
	v_readlane_b32 s2, v253, 0
	v_readlane_b32 s3, v253, 1
	s_nop 4
	global_load_dword v2, v181, s[2:3] sc1
	v_readlane_b32 s2, v253, 2
	v_readlane_b32 s3, v253, 3
	s_nop 4
	global_load_dword v3, v181, s[2:3] sc1
	v_readlane_b32 s2, v253, 4
	v_readlane_b32 s3, v253, 5
	s_nop 4
	global_load_dword v4, v181, s[2:3] sc1
	v_readlane_b32 s2, v253, 6
	v_readlane_b32 s3, v253, 7
	s_nop 4
	global_load_dword v5, v181, s[2:3] sc1
	v_readlane_b32 s2, v253, 8
	v_readlane_b32 s3, v253, 9
	s_nop 4
	global_load_dword v6, v181, s[2:3] sc1
	v_readlane_b32 s2, v253, 10
	v_readlane_b32 s3, v253, 11
	s_nop 4
	global_load_dword v7, v181, s[2:3] sc1
	v_readlane_b32 s2, v253, 12
	v_readlane_b32 s3, v253, 13
	s_nop 4
	global_load_dword v8, v181, s[2:3] sc1
	v_readlane_b32 s2, v253, 14
	v_readlane_b32 s3, v253, 15
	s_nop 4
	global_load_dword v9, v181, s[2:3] sc1
	v_readlane_b32 s2, v253, 16
	v_readlane_b32 s3, v253, 17
	s_nop 4
	global_load_dword v10, v181, s[2:3] sc1
	v_readlane_b32 s2, v253, 18
	v_readlane_b32 s3, v253, 19
	s_nop 4
	global_load_dword v11, v181, s[2:3] sc1
	v_readlane_b32 s2, v253, 20
	v_readlane_b32 s3, v253, 21
	s_nop 4
	global_load_dword v12, v181, s[2:3] sc1
	v_readlane_b32 s2, v253, 22
	v_readlane_b32 s3, v253, 23
	s_nop 4
	global_load_dword v13, v181, s[2:3] sc1
	v_readlane_b32 s2, v253, 24
	v_readlane_b32 s3, v253, 25
	s_nop 4
	global_load_dword v14, v181, s[2:3] sc1
	v_readlane_b32 s2, v253, 26
	v_readlane_b32 s3, v253, 27
	s_nop 4
	global_load_dword v15, v181, s[2:3] sc1
	s_waitcnt vmcnt(0)
	v_add_u32_e32 v16, v1, v0
	v_add_u32_e32 v16, v16, v2
	v_add_u32_e32 v16, v16, v3
	v_add_u32_e32 v16, v16, v4
	v_add_u32_e32 v16, v16, v5
	v_add_u32_e32 v16, v16, v6
	v_add_u32_e32 v16, v16, v7
	v_add_u32_e32 v16, v16, v8
	v_add_u32_e32 v16, v16, v9
	v_add_u32_e32 v16, v16, v10
	v_add_u32_e32 v16, v16, v11
	v_add_u32_e32 v16, v16, v12
	v_add_u32_e32 v16, v16, v13
	v_add_u32_e32 v16, v16, v14
	v_add_u32_e32 v16, v16, v15
	v_cmp_eq_u32_e32 vcc, s38, v16
	s_cbranch_vccnz .LBB0_1192
	s_and_b32 s20, s26, 0xff
	s_cmp_eq_u32 s20, 0
	s_mov_b64 s[20:21], -1
	s_mov_b64 s[24:25], -1
	s_sleep 1
	s_cbranch_scc1 .LBB0_1197
	s_and_b64 vcc, exec, s[24:25]
	s_cbranch_vccz .LBB0_1192
